# P0 rmsnorm: norm weights hoisted out of the row loop + next row prefetched into spare VGPRs (double-buffered rows, counted vmcnt(4))
# speedup vs baseline: 1.2373x; 1.0135x over previous
; DI void rmsnorm_rows(const float* src, const float* w, u16* dst, const float* wabT, float* ab, int bid, int nb) {
;   const int tid = threadIdx.x, lane = tid & 63, wave = tid >> 6;
;   for (int row = bid * 4 + wave; row < T_TOK; row += nb * 4) {
;     const float4* xr = (const float4*)(src + (size_t)row * 1024);
;     float4 v[4]; float ss = 0.f;
; #pragma unroll
;     for (int i = 0; i < 4; i++) { v[i] = xr[lane + 64 * i]; ss += v[i].x * v[i].x + v[i].y * v[i].y + v[i].z * v[i].z + v[i].w * v[i].w; }
;     ss = wsum(ss);
;     const float rstd = rsqrtf(ss * (1.f / 1024.f) + EPSF);
;     float acc[8];
; #pragma unroll
;     for (int j = 0; j < 8; j++) acc[j] = 0.f;
; #pragma unroll
;     for (int i = 0; i < 4; i++) {
;       const int k0 = (lane + 64 * i) * 4;
;       float4 ww = *(const float4*)(w + k0);
.LBB0_16:
	s_or_b64 exec, exec, s[0:1]
	v_lshrrev_b32_e32 v1, 6, v24
	v_lshl_add_u32 v26, s2, 2, v1
	s_movk_i32 s0, 0x4000
	v_cmp_gt_i32_e32 vcc, s0, v26
	s_waitcnt lgkmcnt(0)
	s_barrier
	s_and_saveexec_b64 s[6:7], vcc
	s_cbranch_execz .LBB0_30
	v_mbcnt_lo_u32_b32 v1, -1, 0
	v_mbcnt_hi_u32_b32 v4, -1, v1
	v_and_b32_e32 v1, 64, v4
	v_add_u32_e32 v5, 64, v1
	v_xor_b32_e32 v1, 32, v4
	v_cmp_lt_i32_e32 vcc, v1, v5
	v_xor_b32_e32 v6, 16, v4
	v_and_b32_e32 v3, 63, v24
	v_cndmask_b32_e32 v1, v4, v1, vcc
	v_cmp_lt_i32_e32 vcc, v6, v5
	v_ashrrev_i32_e32 v27, 31, v26
	v_readlane_b32 s4, v253, 8
	v_cndmask_b32_e32 v6, v4, v6, vcc
	v_lshlrev_b32_e32 v25, 2, v6
	v_xor_b32_e32 v6, 8, v4
	v_cmp_lt_i32_e32 vcc, v6, v5
	v_lshlrev_b32_e32 v28, 4, v3
	v_readlane_b32 s16, v253, 15
	v_cndmask_b32_e32 v6, v4, v6, vcc
	v_lshlrev_b32_e32 v40, 2, v6
	v_xor_b32_e32 v6, 4, v4
	v_cmp_lt_i32_e32 vcc, v6, v5
	v_readlane_b32 s5, v253, 9
	v_readlane_b32 s17, v253, 16
	v_cndmask_b32_e32 v6, v4, v6, vcc
	v_lshlrev_b32_e32 v41, 2, v6
	v_xor_b32_e32 v6, 2, v4
	v_cmp_lt_i32_e32 vcc, v6, v5
	s_lshl_b32 s8, s4, 2
	s_mov_b64 s[4:5], 0x800
	v_cndmask_b32_e32 v6, v4, v6, vcc
	v_lshlrev_b32_e32 v42, 2, v6
	v_xor_b32_e32 v6, 1, v4
	v_cmp_lt_i32_e32 vcc, v6, v5
	v_mov_b32_e32 v2, 0
	v_cmp_eq_u32_e64 s[0:1], 0, v3
	v_cndmask_b32_e32 v4, v4, v6, vcc
	v_lshlrev_b32_e32 v43, 2, v4
	v_lshlrev_b64 v[4:5], 12, v[26:27]
	v_or_b32_e32 v4, v4, v28
	v_lshl_add_u64 v[4:5], s[16:17], 0, v[4:5]
	v_lshl_add_u64 v[32:33], v[4:5], 0, s[4:5]
	v_lshlrev_b64 v[4:5], 5, v[26:27]
	v_lshl_add_u64 v[34:35], s[12:13], 0, v[4:5]
	v_lshlrev_b64 v[4:5], 11, v[26:27]
	v_lshl_or_b32 v4, v3, 3, v4
	v_lshl_add_u64 v[4:5], s[46:47], 0, v[4:5]
	s_mov_b64 s[4:5], 0x400
	v_lshl_add_u64 v[36:37], v[4:5], 0, s[4:5]
	s_mov_b64 s[4:5], -1
	v_mov_b32_e32 v29, v2
	v_readlane_b32 s18, v253, 17
	v_readlane_b32 s19, v253, 18
	v_readlane_b32 s20, v253, 19
	v_readlane_b32 s21, v253, 20
	s_ashr_i32 s9, s8, 31
	v_cndmask_b32_e64 v3, 0, 1, s[4:5]
	v_lshlrev_b32_e32 v1, 2, v1
	v_lshl_add_u64 v[30:31], s[18:19], 0, v[28:29]
	s_lshl_b64 s[10:11], s[8:9], 12
	s_lshl_b64 s[16:17], s[8:9], 5
	s_lshl_b64 s[18:19], s[8:9], 11
	s_mov_b64 s[20:21], 0
	v_mov_b32_e32 v27, 0x358637bd
	v_cmp_ne_u32_e64 s[4:5], 1, v3
	v_readlane_b32 s22, v253, 21
	v_readlane_b32 s23, v253, 22
	v_readlane_b32 s24, v253, 23
	v_readlane_b32 s25, v253, 24
	v_readlane_b32 s26, v253, 25
	v_readlane_b32 s27, v253, 26
	v_readlane_b32 s28, v253, 27
	v_readlane_b32 s29, v253, 28
	v_readlane_b32 s30, v253, 29
	v_readlane_b32 s31, v253, 30
	global_load_dwordx4 v[100:103], v[30:31], off
	global_load_dwordx4 v[104:107], v[30:31], off offset:1024
	global_load_dwordx4 v[108:111], v[30:31], off offset:2048
	global_load_dwordx4 v[112:115], v[30:31], off offset:3072
	global_load_dwordx4 v[116:119], v[32:33], off offset:-1024
	global_load_dwordx4 v[120:123], v[32:33], off
	global_load_dwordx4 v[124:127], v[32:33], off offset:1024
	global_load_dwordx4 v[128:131], v[32:33], off offset:-2048
	s_waitcnt vmcnt(0)
	s_branch .LBB0_20

; DI void rmsnorm_rows(const float* src, const float* w, u16* dst, const float* wabT, float* ab, int bid, int nb) {
;     ...
;     const float4* xr = (const float4*)(src + (size_t)row * 1024);
;     float4 v[4]; float ss = 0.f;
; #pragma unroll
;     for (int i = 0; i < 4; i++) { v[i] = xr[lane + 64 * i]; ss += v[i].x * v[i].x + v[i].y * v[i].y + v[i].z * v[i].z + v[i].w * v[i].w; }
;     ss = wsum(ss);
;     const float rstd = rsqrtf(ss * (1.f / 1024.f) + EPSF);
;     float acc[8];
; #pragma unroll
;     for (int j = 0; j < 8; j++) acc[j] = 0.f;
; #pragma unroll
;     for (int i = 0; i < 4; i++) {
;       const int k0 = (lane + 64 * i) * 4;
;       float4 ww = *(const float4*)(w + k0);
;       float y0 = v[i].x * rstd * ww.x, y1 = v[i].y * rstd * ww.y, y2 = v[i].z * rstd * ww.z, y3 = v[i].w * rstd * ww.w;
;       u32x2 pk; pk.x = pack2(y0, y1); pk.y = pack2(y2, y3);
;       *(u32x2*)(dst + (size_t)row * 1024 + k0) = pk;
.LBB0_20:
	s_waitcnt vmcnt(4)
	v_add_u32_e32 v134, s8, v26
	v_lshl_add_u64 v[132:133], v[32:33], 0, s[10:11]
	v_cmp_gt_i32_e32 vcc, 0x4000, v134
	s_nop 0
	v_cndmask_b32_e32 v132, v32, v132, vcc
	v_cndmask_b32_e32 v133, v33, v133, vcc
	v_mov_b32_e32 v20, v116
	v_mov_b32_e32 v21, v117
	v_mov_b32_e32 v22, v118
	v_mov_b32_e32 v23, v119
	global_load_dwordx4 v[116:119], v[132:133], off offset:-1024
	s_waitcnt lgkmcnt(0)
	v_mov_b32_e32 v16, v120
	v_mov_b32_e32 v17, v121
	v_mov_b32_e32 v18, v122
	v_mov_b32_e32 v19, v123
	global_load_dwordx4 v[120:123], v[132:133], off
	v_mov_b32_e32 v12, v124
	v_mov_b32_e32 v13, v125
	v_mov_b32_e32 v14, v126
	v_mov_b32_e32 v15, v127
	global_load_dwordx4 v[124:127], v[132:133], off offset:1024
	s_mov_b32 s3, 0x800000
	v_mov_b32_e32 v51, v21
	v_mov_b32_e32 v6, v17
	v_mov_b32_e32 v7, v13
	v_mov_b32_e32 v4, v16
	v_mov_b32_e32 v5, v12
	v_pk_mul_f32 v[6:7], v[6:7], v[6:7]
	v_mov_b32_e32 v49, v20
	v_pk_fma_f32 v[4:5], v[4:5], v[4:5], v[6:7]
	v_mov_b32_e32 v6, v18
	v_mov_b32_e32 v7, v14
	v_pk_fma_f32 v[4:5], v[6:7], v[6:7], v[4:5]
	v_mov_b32_e32 v6, v19
	v_mov_b32_e32 v7, v15
	v_pk_fma_f32 v[38:39], v[6:7], v[6:7], v[4:5]
	v_mov_b32_e32 v4, v128
	v_mov_b32_e32 v5, v129
	v_mov_b32_e32 v6, v130
	v_mov_b32_e32 v7, v131
	global_load_dwordx4 v[128:131], v[132:133], off offset:-2048
	v_mov_b32_e32 v8, v100
	v_mov_b32_e32 v9, v101
	v_mov_b32_e32 v10, v102
	v_mov_b32_e32 v11, v103
	v_mov_b32_e32 v45, v22
	v_mov_b32_e32 v47, v23
	v_mov_b32_e32 v50, v5
	v_mov_b32_e32 v48, v4
	v_pk_mul_f32 v[50:51], v[50:51], v[50:51]
	v_mov_b32_e32 v44, v6
	v_pk_fma_f32 v[48:49], v[48:49], v[48:49], v[50:51]
	v_mov_b32_e32 v46, v7
	v_pk_fma_f32 v[44:45], v[44:45], v[44:45], v[48:49]
	s_nop 0
	v_pk_fma_f32 v[44:45], v[46:47], v[46:47], v[44:45]
	s_nop 0
	v_add_f32_e32 v3, v44, v45
	v_add_f32_e32 v3, v3, v38
	v_add_f32_e32 v3, v3, v39
	ds_bpermute_b32 v29, v1, v3
	s_waitcnt lgkmcnt(0)
	v_add_f32_e32 v3, v3, v29
	ds_bpermute_b32 v29, v25, v3
	s_waitcnt lgkmcnt(0)
	v_add_f32_e32 v3, v3, v29
	ds_bpermute_b32 v29, v40, v3
	s_waitcnt lgkmcnt(0)
	v_add_f32_e32 v3, v3, v29
	ds_bpermute_b32 v29, v41, v3
	s_waitcnt lgkmcnt(0)
	v_add_f32_e32 v3, v3, v29
	ds_bpermute_b32 v29, v42, v3
	s_waitcnt lgkmcnt(0)
	v_add_f32_e32 v3, v3, v29
	ds_bpermute_b32 v29, v43, v3
	s_waitcnt lgkmcnt(0)
	v_add_f32_e32 v3, v3, v29
	v_fmamk_f32 v3, v3, 0x3a800000, v27
	v_cmp_gt_f32_e32 vcc, s3, v3
	v_mul_f32_e32 v29, 0x4b800000, v3
	s_nop 0
	v_cndmask_b32_e32 v3, v3, v29, vcc
	v_rsq_f32_e32 v3, v3
	s_nop 0
	v_mul_f32_e32 v29, 0x45800000, v3
	v_cndmask_b32_e32 v38, v3, v29, vcc
	v_pk_mul_f32 v[4:5], v[4:5], v[38:39] op_sel_hi:[1,0]
	v_pk_mul_f32 v[6:7], v[6:7], v[38:39] op_sel_hi:[1,0]
	v_pk_mul_f32 v[4:5], v[8:9], v[4:5]
	v_pk_mul_f32 v[6:7], v[10:11], v[6:7]
	v_cvt_pk_bf16_f32 v8, v4, v5
	v_cvt_pk_bf16_f32 v9, v6, v7
	s_and_b64 vcc, exec, s[4:5]
	global_store_dwordx2 v[36:37], v[8:9], off offset:-1024
	s_cbranch_vccnz .LBB0_22
	ds_read_b128 v[8:11], v28 offset:256
	ds_read_b128 v[44:47], v28 offset:4352
	ds_read_b128 v[48:51], v28 offset:8448
	ds_read_b128 v[52:55], v28 offset:12544
	s_waitcnt lgkmcnt(3)
	v_mov_b32_e32 v62, v10
	s_waitcnt lgkmcnt(2)
	v_pk_mov_b32 v[60:61], v[8:9], v[44:45] op_sel:[1,0]
	v_mov_b32_e32 v9, v45
	v_pk_mul_f32 v[44:45], v[4:5], v[8:9]
	v_mov_b32_e32 v63, v46
	v_mov_b32_e32 v46, v11
	ds_read_b128 v[8:11], v28 offset:16640
	ds_read_b128 v[56:59], v28 offset:20736
	s_waitcnt lgkmcnt(2)
	v_pk_mov_b32 v[64:65], v[48:49], v[52:53] op_sel:[1,0]
	v_mov_b32_e32 v49, v53
	v_pk_mul_f32 v[52:53], v[4:5], v[48:49]
	v_mov_b32_e32 v66, v50
	s_waitcnt lgkmcnt(0)
	v_pk_mov_b32 v[68:69], v[8:9], v[56:57] op_sel:[1,0]
	v_mov_b32_e32 v9, v57
	v_mov_b32_e32 v67, v54
	v_mov_b32_e32 v54, v51
	v_pk_mul_f32 v[56:57], v[4:5], v[8:9]
	ds_read_b128 v[48:51], v28 offset:24832
	v_mov_b32_e32 v70, v10
	v_mov_b32_e32 v71, v58
	v_mov_b32_e32 v58, v11
	ds_read_b128 v[8:11], v28 offset:28928
	s_waitcnt lgkmcnt(1)
	v_mul_f32_e32 v48, v4, v48
	v_mul_f32_e32 v72, v5, v49
	v_mul_f32_e32 v50, v6, v50
	v_mul_f32_e32 v74, v7, v51
	s_waitcnt lgkmcnt(0)
	v_pk_mul_f32 v[8:9], v[4:5], v[8:9]
	v_pk_mul_f32 v[10:11], v[6:7], v[10:11]
	v_mov_b32_e32 v49, v8
	v_mov_b32_e32 v73, v9
	v_mov_b32_e32 v51, v10
	v_mov_b32_e32 v75, v11
	v_pk_fma_f32 v[8:9], v[4:5], v[60:61], v[44:45] op_sel:[1,0,0] op_sel_hi:[0,1,1]
	v_pk_fma_f32 v[10:11], v[4:5], v[64:65], v[52:53] op_sel:[1,0,0] op_sel_hi:[0,1,1]
	v_pk_fma_f32 v[4:5], v[4:5], v[68:69], v[56:57] op_sel:[1,0,0] op_sel_hi:[0,1,1]
	v_pk_add_f32 v[44:45], v[48:49], v[72:73]
	v_pk_fma_f32 v[8:9], v[6:7], v[62:63], v[8:9] op_sel_hi:[0,1,1]
	v_pk_fma_f32 v[10:11], v[6:7], v[66:67], v[10:11] op_sel_hi:[0,1,1]
	v_pk_fma_f32 v[4:5], v[6:7], v[70:71], v[4:5] op_sel_hi:[0,1,1]
	v_pk_add_f32 v[44:45], v[44:45], v[50:51]
	v_pk_fma_f32 v[46:47], v[6:7], v[46:47], v[8:9] op_sel:[1,0,0]
	v_pk_fma_f32 v[10:11], v[6:7], v[54:55], v[10:11] op_sel:[1,0,0]
	v_pk_fma_f32 v[4:5], v[6:7], v[58:59], v[4:5] op_sel:[1,0,0]
	v_pk_add_f32 v[44:45], v[44:45], v[74:75]
	v_pk_add_f32 v[8:9], v[4:5], 0 op_sel_hi:[1,0]
	v_pk_add_f32 v[6:7], v[10:11], 0 op_sel_hi:[1,0]
	v_pk_add_f32 v[4:5], v[46:47], 0 op_sel_hi:[1,0]
	v_pk_add_f32 v[10:11], v[44:45], 0 op_sel_hi:[1,0]
	s_branch .LBB0_23

; DI void rmsnorm_rows(const float* src, const float* w, u16* dst, const float* wabT, float* ab, int bid, int nb) {
;     ...
;     for (int i = 0; i < 4; i++) {
;       const int k0 = (lane + 64 * i) * 4;
;       float4 ww = *(const float4*)(w + k0);
;       float y0 = v[i].x * rstd * ww.x, y1 = v[i].y * rstd * ww.y, y2 = v[i].z * rstd * ww.z, y3 = v[i].w * rstd * ww.w;
;       u32x2 pk; pk.x = pack2(y0, y1); pk.y = pack2(y2, y3);
;       *(u32x2*)(dst + (size_t)row * 1024 + k0) = pk;
;       if (wabT) {
; #pragma unroll
;         for (int j = 0; j < 8; j++) {
;           float4 wj = *(const float4*)(wabT + j * 1024 + k0);
;           acc[j] += y0 * wj.x + y1 * wj.y + y2 * wj.z + y3 * wj.w;
;         }
;       }
.LBB0_23:
	v_mov_b32_e32 v44, v104
	v_mov_b32_e32 v45, v105
	v_mov_b32_e32 v46, v106
	v_mov_b32_e32 v47, v107
	v_mov_b32_e32 v39, v38
	v_pk_mul_f32 v[20:21], v[20:21], v[38:39]
	v_pk_mul_f32 v[48:49], v[22:23], v[38:39]
	s_and_b64 vcc, exec, s[4:5]
	v_pk_mul_f32 v[22:23], v[20:21], v[44:45]
	v_pk_mul_f32 v[20:21], v[48:49], v[46:47]
	v_cvt_pk_bf16_f32 v44, v22, v23
	v_cvt_pk_bf16_f32 v45, v20, v21
	global_store_dwordx2 v[36:37], v[44:45], off offset:-512
	s_cbranch_vccnz .LBB0_25
	ds_read_b128 v[44:47], v28 offset:1280
	ds_read_b128 v[48:51], v28 offset:5376
	ds_read_b128 v[52:55], v28 offset:9472
	ds_read_b128 v[56:59], v28 offset:13568
	s_waitcnt lgkmcnt(3)
	v_mov_b32_e32 v66, v46
	s_waitcnt lgkmcnt(2)
	v_pk_mov_b32 v[64:65], v[44:45], v[48:49] op_sel:[1,0]
	v_mov_b32_e32 v45, v49
	v_pk_mul_f32 v[48:49], v[22:23], v[44:45]
	v_mov_b32_e32 v67, v50
	v_mov_b32_e32 v50, v47
	ds_read_b128 v[44:47], v28 offset:17664
	ds_read_b128 v[60:63], v28 offset:21760
	s_waitcnt lgkmcnt(2)
	v_pk_mov_b32 v[68:69], v[52:53], v[56:57] op_sel:[1,0]
	v_mov_b32_e32 v53, v57
	v_pk_mul_f32 v[56:57], v[22:23], v[52:53]
	v_mov_b32_e32 v70, v54
	s_waitcnt lgkmcnt(0)
	v_pk_mov_b32 v[72:73], v[44:45], v[60:61] op_sel:[1,0]
	v_mov_b32_e32 v45, v61
	v_mov_b32_e32 v71, v58
	v_mov_b32_e32 v58, v55
	v_pk_mul_f32 v[60:61], v[22:23], v[44:45]
	ds_read_b128 v[52:55], v28 offset:25856
	v_mov_b32_e32 v74, v46
	v_mov_b32_e32 v75, v62
	v_mov_b32_e32 v62, v47
	ds_read_b128 v[44:47], v28 offset:29952
	s_waitcnt lgkmcnt(1)
	v_mul_f32_e32 v52, v22, v52
	v_mul_f32_e32 v76, v23, v53
	v_mul_f32_e32 v54, v20, v54
	v_mul_f32_e32 v78, v21, v55
	s_waitcnt lgkmcnt(0)
	v_pk_mul_f32 v[44:45], v[22:23], v[44:45]
	v_pk_mul_f32 v[46:47], v[20:21], v[46:47]
	v_mov_b32_e32 v53, v44
	v_mov_b32_e32 v77, v45
	v_mov_b32_e32 v55, v46
	v_mov_b32_e32 v79, v47
	v_pk_fma_f32 v[44:45], v[22:23], v[64:65], v[48:49] op_sel:[1,0,0] op_sel_hi:[0,1,1]
	v_pk_fma_f32 v[46:47], v[22:23], v[68:69], v[56:57] op_sel:[1,0,0] op_sel_hi:[0,1,1]
	v_pk_fma_f32 v[22:23], v[22:23], v[72:73], v[60:61] op_sel:[1,0,0] op_sel_hi:[0,1,1]
	v_pk_add_f32 v[48:49], v[52:53], v[76:77]
	v_pk_fma_f32 v[44:45], v[20:21], v[66:67], v[44:45] op_sel_hi:[0,1,1]
	v_pk_fma_f32 v[46:47], v[20:21], v[70:71], v[46:47] op_sel_hi:[0,1,1]
	v_pk_fma_f32 v[22:23], v[20:21], v[74:75], v[22:23] op_sel_hi:[0,1,1]
	v_pk_add_f32 v[48:49], v[48:49], v[54:55]
	v_pk_fma_f32 v[44:45], v[20:21], v[50:51], v[44:45] op_sel:[1,0,0]
	v_pk_fma_f32 v[46:47], v[20:21], v[58:59], v[46:47] op_sel:[1,0,0]
	v_pk_fma_f32 v[20:21], v[20:21], v[62:63], v[22:23] op_sel:[1,0,0]
	v_pk_add_f32 v[22:23], v[48:49], v[78:79]
	v_pk_add_f32 v[8:9], v[8:9], v[20:21]
	v_pk_add_f32 v[6:7], v[6:7], v[46:47]
	v_pk_add_f32 v[4:5], v[4:5], v[44:45]
	v_pk_add_f32 v[10:11], v[10:11], v[22:23]
.LBB0_25:
	v_mov_b32_e32 v20, v108
	v_mov_b32_e32 v21, v109
	v_mov_b32_e32 v22, v110
	v_mov_b32_e32 v23, v111
	v_pk_mul_f32 v[16:17], v[16:17], v[38:39]
	v_pk_mul_f32 v[44:45], v[18:19], v[38:39]
	s_and_b64 vcc, exec, s[4:5]
	v_pk_mul_f32 v[18:19], v[16:17], v[20:21]
	v_pk_mul_f32 v[16:17], v[44:45], v[22:23]
	v_cvt_pk_bf16_f32 v20, v18, v19
	v_cvt_pk_bf16_f32 v21, v16, v17
	global_store_dwordx2 v[36:37], v[20:21], off
	s_cbranch_vccnz .LBB0_27
	ds_read_b128 v[20:23], v28 offset:2304
	ds_read_b128 v[44:47], v28 offset:6400
	ds_read_b128 v[48:51], v28 offset:10496
	ds_read_b128 v[52:55], v28 offset:14592
	s_waitcnt lgkmcnt(3)
	v_mov_b32_e32 v62, v22
	s_waitcnt lgkmcnt(2)
	v_pk_mov_b32 v[60:61], v[20:21], v[44:45] op_sel:[1,0]
	v_mov_b32_e32 v21, v45
	v_pk_mul_f32 v[44:45], v[18:19], v[20:21]
	v_mov_b32_e32 v63, v46
	v_mov_b32_e32 v46, v23
	ds_read_b128 v[20:23], v28 offset:18688
	ds_read_b128 v[56:59], v28 offset:22784
	s_waitcnt lgkmcnt(2)
	v_pk_mov_b32 v[64:65], v[48:49], v[52:53] op_sel:[1,0]
	v_mov_b32_e32 v49, v53
	v_pk_mul_f32 v[52:53], v[18:19], v[48:49]
	v_mov_b32_e32 v66, v50
	s_waitcnt lgkmcnt(0)
	v_pk_mov_b32 v[68:69], v[20:21], v[56:57] op_sel:[1,0]
	v_mov_b32_e32 v21, v57
	v_mov_b32_e32 v67, v54
	v_mov_b32_e32 v54, v51
	v_pk_mul_f32 v[56:57], v[18:19], v[20:21]
	ds_read_b128 v[48:51], v28 offset:26880
	v_mov_b32_e32 v70, v22
	v_mov_b32_e32 v71, v58
	v_mov_b32_e32 v58, v23
	ds_read_b128 v[20:23], v28 offset:30976
	s_waitcnt lgkmcnt(1)
	v_mul_f32_e32 v48, v18, v48
	v_mul_f32_e32 v72, v19, v49
	v_mul_f32_e32 v50, v16, v50
	v_mul_f32_e32 v74, v17, v51
	s_waitcnt lgkmcnt(0)
	v_pk_mul_f32 v[20:21], v[18:19], v[20:21]
	v_pk_mul_f32 v[22:23], v[16:17], v[22:23]
	v_mov_b32_e32 v49, v20
	v_mov_b32_e32 v73, v21
	v_mov_b32_e32 v51, v22
	v_mov_b32_e32 v75, v23
	v_pk_fma_f32 v[20:21], v[18:19], v[60:61], v[44:45] op_sel:[1,0,0] op_sel_hi:[0,1,1]
	v_pk_fma_f32 v[22:23], v[18:19], v[64:65], v[52:53] op_sel:[1,0,0] op_sel_hi:[0,1,1]
	v_pk_fma_f32 v[18:19], v[18:19], v[68:69], v[56:57] op_sel:[1,0,0] op_sel_hi:[0,1,1]
	v_pk_add_f32 v[44:45], v[48:49], v[72:73]
	v_pk_fma_f32 v[20:21], v[16:17], v[62:63], v[20:21] op_sel_hi:[0,1,1]
	v_pk_fma_f32 v[22:23], v[16:17], v[66:67], v[22:23] op_sel_hi:[0,1,1]
	v_pk_fma_f32 v[18:19], v[16:17], v[70:71], v[18:19] op_sel_hi:[0,1,1]
	v_pk_add_f32 v[44:45], v[44:45], v[50:51]
	v_pk_fma_f32 v[20:21], v[16:17], v[46:47], v[20:21] op_sel:[1,0,0]
	v_pk_fma_f32 v[22:23], v[16:17], v[54:55], v[22:23] op_sel:[1,0,0]
	v_pk_fma_f32 v[16:17], v[16:17], v[58:59], v[18:19] op_sel:[1,0,0]
	v_pk_add_f32 v[18:19], v[44:45], v[74:75]
	v_pk_add_f32 v[8:9], v[8:9], v[16:17]
	v_pk_add_f32 v[6:7], v[6:7], v[22:23]
	v_pk_add_f32 v[4:5], v[4:5], v[20:21]
	v_pk_add_f32 v[10:11], v[10:11], v[18:19]
; DI void rmsnorm_rows(const float* src, const float* w, u16* dst, const float* wabT, float* ab, int bid, int nb) {
;     ...
;     for (int i = 0; i < 4; i++) {
;       const int k0 = (lane + 64 * i) * 4;
;       float4 ww = *(const float4*)(w + k0);
;       float y0 = v[i].x * rstd * ww.x, y1 = v[i].y * rstd * ww.y, y2 = v[i].z * rstd * ww.z, y3 = v[i].w * rstd * ww.w;
;       u32x2 pk; pk.x = pack2(y0, y1); pk.y = pack2(y2, y3);
;       *(u32x2*)(dst + (size_t)row * 1024 + k0) = pk;
;       if (wabT) {
; #pragma unroll
;         for (int j = 0; j < 8; j++) {
;           float4 wj = *(const float4*)(wabT + j * 1024 + k0);
;           acc[j] += y0 * wj.x + y1 * wj.y + y2 * wj.z + y3 * wj.w;
;         }
;       }
;     }
;     if (wabT) {
; #pragma unroll
;       for (int j = 0; j < 8; j++) acc[j] = wsum(acc[j]);
;       if (lane == 0) {
;         *(float4*)(ab + (size_t)row * 8) = make_float4(acc[0], acc[1], acc[2], acc[3]);
;         *(float4*)(ab + (size_t)row * 8 + 4) = make_float4(acc[4], acc[5], acc[6], acc[7]);
;       }
.LBB0_27:
	v_mov_b32_e32 v16, v112
	v_mov_b32_e32 v17, v113
	v_mov_b32_e32 v18, v114
	v_mov_b32_e32 v19, v115
	v_pk_mul_f32 v[12:13], v[12:13], v[38:39]
	v_pk_mul_f32 v[20:21], v[14:15], v[38:39]
	s_and_b64 vcc, exec, s[4:5]
	v_pk_mul_f32 v[14:15], v[12:13], v[16:17]
	v_pk_mul_f32 v[12:13], v[20:21], v[18:19]
	v_cvt_pk_bf16_f32 v16, v14, v15
	v_cvt_pk_bf16_f32 v17, v12, v13
	global_store_dwordx2 v[36:37], v[16:17], off offset:512
	s_cbranch_vccnz .LBB0_19
	ds_read_b128 v[16:19], v28 offset:3328
	ds_read_b128 v[20:23], v28 offset:7424
	s_waitcnt lgkmcnt(0)
	v_pk_mov_b32 v[38:39], v[16:17], v[20:21] op_sel:[1,0]
	v_mov_b32_e32 v17, v21
	v_pk_mul_f32 v[16:17], v[14:15], v[16:17]
	v_mov_b32_e32 v20, v18
	v_mov_b32_e32 v21, v22
	v_pk_fma_f32 v[16:17], v[14:15], v[38:39], v[16:17] op_sel:[1,0,0] op_sel_hi:[0,1,1]
	v_pk_fma_f32 v[16:17], v[12:13], v[20:21], v[16:17] op_sel_hi:[0,1,1]
	v_mov_b32_e32 v22, v19
	v_pk_fma_f32 v[16:17], v[12:13], v[22:23], v[16:17] op_sel:[1,0,0]
	s_nop 0
	v_pk_add_f32 v[4:5], v[4:5], v[16:17]
	ds_read_b128 v[16:19], v28 offset:11520
	ds_read_b128 v[20:23], v28 offset:15616
	ds_bpermute_b32 v38, v1, v4
	ds_bpermute_b32 v39, v1, v5
	s_waitcnt lgkmcnt(2)
	v_pk_mov_b32 v[44:45], v[16:17], v[20:21] op_sel:[1,0]
	v_mov_b32_e32 v17, v21
	v_pk_mul_f32 v[16:17], v[14:15], v[16:17]
	v_mov_b32_e32 v20, v18
	v_pk_fma_f32 v[16:17], v[14:15], v[44:45], v[16:17] op_sel:[1,0,0] op_sel_hi:[0,1,1]
	v_mov_b32_e32 v21, v22
	v_pk_fma_f32 v[16:17], v[12:13], v[20:21], v[16:17] op_sel_hi:[0,1,1]
	v_mov_b32_e32 v22, v19
	v_pk_fma_f32 v[16:17], v[12:13], v[22:23], v[16:17] op_sel:[1,0,0]
	s_waitcnt lgkmcnt(0)
	v_pk_add_f32 v[4:5], v[4:5], v[38:39]
	v_pk_add_f32 v[6:7], v[6:7], v[16:17]
	ds_bpermute_b32 v38, v25, v4
	ds_bpermute_b32 v39, v25, v5
	ds_bpermute_b32 v16, v1, v6
	ds_bpermute_b32 v17, v1, v7
	s_waitcnt lgkmcnt(2)
	v_pk_add_f32 v[4:5], v[4:5], v[38:39]
	ds_bpermute_b32 v18, v40, v4
	s_waitcnt lgkmcnt(1)
	v_pk_add_f32 v[6:7], v[6:7], v[16:17]
	ds_bpermute_b32 v19, v40, v5
	ds_bpermute_b32 v16, v25, v6
	ds_bpermute_b32 v17, v25, v7
	s_waitcnt lgkmcnt(2)
	v_pk_add_f32 v[4:5], v[4:5], v[18:19]
	ds_bpermute_b32 v18, v41, v4
	s_waitcnt lgkmcnt(1)
	v_pk_add_f32 v[6:7], v[6:7], v[16:17]
	ds_bpermute_b32 v19, v41, v5
	ds_bpermute_b32 v16, v40, v6
	ds_bpermute_b32 v17, v40, v7
	s_waitcnt lgkmcnt(2)
	v_pk_add_f32 v[4:5], v[4:5], v[18:19]
	ds_bpermute_b32 v38, v42, v4
	s_waitcnt lgkmcnt(1)
	v_pk_add_f32 v[44:45], v[6:7], v[16:17]
	ds_bpermute_b32 v39, v42, v5
	ds_bpermute_b32 v46, v41, v44
	ds_bpermute_b32 v47, v41, v45
	ds_read_b128 v[16:19], v28 offset:19712
	ds_read_b128 v[20:23], v28 offset:23808
	s_waitcnt lgkmcnt(4)
	v_pk_add_f32 v[4:5], v[4:5], v[38:39]
	ds_bpermute_b32 v6, v43, v4
	s_waitcnt lgkmcnt(3)
	v_pk_add_f32 v[38:39], v[44:45], v[46:47]
	s_waitcnt lgkmcnt(1)
	v_pk_mov_b32 v[44:45], v[16:17], v[20:21] op_sel:[1,0]
	v_mov_b32_e32 v17, v21
	v_pk_mul_f32 v[16:17], v[14:15], v[16:17]
	v_mov_b32_e32 v20, v18
	v_pk_fma_f32 v[16:17], v[14:15], v[44:45], v[16:17] op_sel:[1,0,0] op_sel_hi:[0,1,1]
	v_mov_b32_e32 v21, v22
	v_pk_fma_f32 v[20:21], v[12:13], v[20:21], v[16:17] op_sel_hi:[0,1,1]
	v_mov_b32_e32 v22, v19
	ds_read_b128 v[16:19], v28 offset:27904
	ds_read_b128 v[44:47], v28 offset:32000
	v_pk_fma_f32 v[20:21], v[12:13], v[22:23], v[20:21] op_sel:[1,0,0]
	ds_bpermute_b32 v7, v43, v5
	v_pk_add_f32 v[8:9], v[8:9], v[20:21]
	ds_bpermute_b32 v20, v1, v8
	s_waitcnt lgkmcnt(2)
	v_pk_mov_b32 v[22:23], v[16:17], v[44:45] op_sel:[1,0]
	v_mov_b32_e32 v17, v45
	v_pk_mul_f32 v[16:17], v[14:15], v[16:17]
	ds_bpermute_b32 v21, v1, v9
	v_pk_fma_f32 v[14:15], v[14:15], v[22:23], v[16:17] op_sel:[1,0,0] op_sel_hi:[0,1,1]
	v_mov_b32_e32 v16, v18
	v_mov_b32_e32 v17, v46
	v_pk_fma_f32 v[14:15], v[12:13], v[16:17], v[14:15] op_sel_hi:[0,1,1]
	v_mov_b32_e32 v46, v19
	v_pk_fma_f32 v[12:13], v[12:13], v[46:47], v[14:15] op_sel:[1,0,0]
	s_waitcnt lgkmcnt(0)
	v_pk_add_f32 v[8:9], v[8:9], v[20:21]
	v_pk_add_f32 v[10:11], v[10:11], v[12:13]
	ds_bpermute_b32 v12, v1, v10
	ds_bpermute_b32 v13, v1, v11
	ds_bpermute_b32 v16, v25, v8
	ds_bpermute_b32 v17, v25, v9
	ds_bpermute_b32 v14, v42, v38
	ds_bpermute_b32 v15, v42, v39
	s_waitcnt lgkmcnt(4)
	v_pk_add_f32 v[10:11], v[10:11], v[12:13]
	ds_bpermute_b32 v12, v25, v10
	ds_bpermute_b32 v13, v25, v11
	s_waitcnt lgkmcnt(4)
	v_pk_add_f32 v[16:17], v[8:9], v[16:17]
	ds_bpermute_b32 v18, v40, v16
	ds_bpermute_b32 v19, v40, v17
	s_waitcnt lgkmcnt(4)
	v_pk_add_f32 v[8:9], v[38:39], v[14:15]
	s_waitcnt lgkmcnt(2)
	v_pk_add_f32 v[10:11], v[10:11], v[12:13]
	ds_bpermute_b32 v12, v40, v10
	ds_bpermute_b32 v13, v40, v11
	s_waitcnt lgkmcnt(2)
	v_pk_add_f32 v[14:15], v[16:17], v[18:19]
	ds_bpermute_b32 v16, v41, v14
	ds_bpermute_b32 v17, v41, v15
	s_waitcnt lgkmcnt(2)
	v_pk_add_f32 v[12:13], v[10:11], v[12:13]
	ds_bpermute_b32 v18, v41, v12
	ds_bpermute_b32 v19, v41, v13
	s_waitcnt lgkmcnt(2)
	v_pk_add_f32 v[14:15], v[14:15], v[16:17]
	ds_bpermute_b32 v16, v42, v14
	ds_bpermute_b32 v17, v42, v15
	ds_bpermute_b32 v10, v43, v8
	s_waitcnt lgkmcnt(3)
	v_pk_add_f32 v[18:19], v[12:13], v[18:19]
	ds_bpermute_b32 v20, v42, v18
	ds_bpermute_b32 v21, v42, v19
	s_waitcnt lgkmcnt(3)
	v_pk_add_f32 v[12:13], v[14:15], v[16:17]
	ds_bpermute_b32 v11, v43, v9
	ds_bpermute_b32 v14, v43, v12
	ds_bpermute_b32 v15, v43, v13
	s_waitcnt lgkmcnt(3)
	v_pk_add_f32 v[16:17], v[18:19], v[20:21]
	ds_bpermute_b32 v18, v43, v16
	ds_bpermute_b32 v19, v43, v17
	s_and_saveexec_b64 s[22:23], s[0:1]
	s_cbranch_execz .LBB0_18
	v_pk_add_f32 v[4:5], v[4:5], v[6:7]
	s_waitcnt lgkmcnt(4)
	v_pk_add_f32 v[6:7], v[8:9], v[10:11]
	global_store_dwordx4 v[34:35], v[4:7], off
	s_waitcnt lgkmcnt(2)
	s_nop 0
	v_pk_add_f32 v[4:5], v[12:13], v[14:15]
	s_waitcnt lgkmcnt(0)
	v_pk_add_f32 v[6:7], v[16:17], v[18:19]
	global_store_dwordx4 v[34:35], v[4:7], off offset:16
	s_branch .LBB0_18
